# phase 8: sample and pad rows also through the new path, spread over 64 workgroups (no fifth-step tail)
# speedup vs baseline: 1.1453x; 1.0033x over previous
.LBB0_1867:
	s_cmp_lt_i32 s4, 9
	s_cselect_b64 s[0:1], -1, 0
	s_cmp_gt_i32 s5, 8
	s_cselect_b64 s[2:3], -1, 0
	s_and_b64 s[0:1], s[0:1], s[2:3]
	s_andn2_b64 vcc, exec, s[0:1]
	s_cbranch_vccnz .LBB0_1983
	s_lshl_b32 s8, s28, 3
	s_cmp_lg_u32 s88, 0x100
	s_cbranch_scc1 .Lpost_orig
	v_and_b32_e32 v2, 63, v34
	v_lshrrev_b32_e32 v3, 6, v34
	v_and_b32_e32 v4, 31, v2
	v_lshlrev_b32_e32 v5, 7, v3
	v_lshl_add_u32 v6, v4, 2, v5
	v_and_b32_e32 v7, 15, v2
	v_lshl_add_u32 v8, v7, 3, v5
	v_lshrrev_b32_e32 v9, 5, v2
	v_lshrrev_b32_e32 v10, 4, v2
	v_lshrrev_b32_e32 v11, 4, v4
	v_lshl_add_u32 v11, v3, 1, v11
	v_lshlrev_b32_e32 v12, 1, v6
	v_lshlrev_b32_e32 v13, 1, v8
	v_lshl_add_u32 v68, v9, 11, v12
	v_mul_u32_u24_e32 v14, 0x5c00, v9
	v_add_u32_e32 v69, v14, v12
	v_add_u32_e32 v69, 0x1000, v69
	v_lshlrev_b32_e32 v14, 2, v11
	v_lshl_add_u32 v71, v9, 6, v14
	v_lshl_add_u32 v72, v9, 12, v12
	v_lshl_add_u32 v73, v10, 11, v13
	v_mul_u32_u24_e32 v14, 0x5c00, v10
	v_add_u32_e32 v74, v14, v13
	v_add_u32_e32 v74, 0x3400, v74
	v_lshl_add_u32 v75, v10, 12, v13
	v_add_u32_e32 v75, 0x800, v75
	v_mul_u32_u24_e32 v14, 0x3480, v9
	v_lshl_add_u32 v70, v6, 2, v14
	v_add_u32_e32 v70, 0x2000, v70
	v_readlane_b32 s12, v254, 29
	v_readlane_b32 s13, v254, 30
	v_readlane_b32 s14, v254, 31
	v_readlane_b32 s15, v254, 32
	v_readlane_b32 s16, v254, 33
	v_readlane_b32 s17, v254, 34
	v_readlane_b32 s18, v254, 35
	v_readlane_b32 s19, v254, 36
	v_lshlrev_b32_e32 v14, 2, v6
	v_lshlrev_b32_e32 v15, 2, v8
	s_nop 4
	global_load_dwordx4 v[40:43], v14, s[12:13]
	global_load_dwordx4 v[44:47], v14, s[14:15]
	global_load_dwordx4 v[52:55], v15, s[16:17]
	global_load_dwordx4 v[56:59], v15, s[16:17] offset:16
	global_load_dwordx4 v[60:63], v15, s[18:19]
	global_load_dwordx4 v[64:67], v15, s[18:19] offset:16
	v_add_u32_e32 v14, 0x2000, v14
	global_load_dwordx4 v[48:51], v14, s[58:59]
	s_lshl_b32 s0, s28, 14
	s_mul_i32 s1, s28, 0x2e000
	s_lshl_b32 s2, s28, 9
	s_lshl_b32 s3, s28, 15
	s_add_u32 s10, s34, 0x9122200
	s_addc_u32 s11, s35, 0
	s_add_u32 s10, s10, s0
	s_addc_u32 s11, s11, 0
	s_add_u32 s12, s34, 0x1d2e2200
	s_addc_u32 s13, s35, 0
	s_add_u32 s12, s12, s0
	s_addc_u32 s13, s13, 0
	s_add_u32 s14, s34, 0xd322200
	s_addc_u32 s15, s35, 0
	s_add_u32 s14, s14, s1
	s_addc_u32 s15, s15, 0
	s_sub_u32 s16, s14, 0x5c00
	s_subb_u32 s17, s15, 0
	s_add_u32 s18, s34, 0x8a70200
	s_addc_u32 s19, s35, 0
	s_add_u32 s18, s18, s2
	s_addc_u32 s19, s19, 0
	s_add_u32 s20, s34, 0xb222200
	s_addc_u32 s21, s35, 0
	s_add_u32 s20, s20, s3
	s_addc_u32 s21, s21, 0
	s_add_u32 s22, s82, s0
	s_addc_u32 s23, s83, 0
	s_mov_b64 s[24:25], s[14:15]
	s_mov_b64 s[26:27], s[20:21]
	s_cmp_eq_u32 s28, 0
	s_cselect_b32 s44, -1, 0
	s_mov_b32 s45, 0
	s_mov_b32 s30, 4
	global_load_dwordx2 v[80:81], v68, s[10:11] nt
	global_load_dwordx2 v[82:83], v69, s[14:15]
	global_load_dwordx2 v[84:85], v69, s[16:17]
	global_load_dword v88, v71, s[18:19]
	global_load_dwordx2 v[86:87], v68, s[12:13] nt
	s_add_u32 s10, s10, 0x1000
	s_addc_u32 s11, s11, 0
	s_add_u32 s12, s12, 0x1000
	s_addc_u32 s13, s13, 0
	s_add_u32 s14, s14, 0xb800
	s_addc_u32 s15, s15, 0
	s_add_u32 s16, s16, 0xb800
	s_addc_u32 s17, s17, 0
	s_add_u32 s18, s18, 0x80
	s_addc_u32 s19, s19, 0
	global_load_dwordx2 v[90:91], v68, s[10:11] nt
	global_load_dwordx2 v[92:93], v69, s[14:15]
	global_load_dwordx2 v[94:95], v69, s[16:17]
	global_load_dword v98, v71, s[18:19]
	global_load_dwordx2 v[96:97], v68, s[12:13] nt
	s_add_u32 s10, s10, 0x1000
	s_addc_u32 s11, s11, 0
	s_add_u32 s12, s12, 0x1000
	s_addc_u32 s13, s13, 0
	s_add_u32 s14, s14, 0xb800
	s_addc_u32 s15, s15, 0
	s_add_u32 s16, s16, 0xb800
	s_addc_u32 s17, s17, 0
	s_add_u32 s18, s18, 0x80
	s_addc_u32 s19, s19, 0
	global_load_dwordx2 v[100:101], v68, s[10:11] nt
	global_load_dwordx2 v[102:103], v69, s[14:15]
	global_load_dwordx2 v[104:105], v69, s[16:17]
	global_load_dword v108, v71, s[18:19]
	global_load_dwordx2 v[106:107], v68, s[12:13] nt
	s_add_u32 s10, s10, 0x1000
	s_addc_u32 s11, s11, 0
	s_add_u32 s12, s12, 0x1000
	s_addc_u32 s13, s13, 0
	s_add_u32 s14, s14, 0xb800
	s_addc_u32 s15, s15, 0
	s_add_u32 s16, s16, 0xb800
	s_addc_u32 s17, s17, 0
	s_add_u32 s18, s18, 0x80
	s_addc_u32 s19, s19, 0
	global_load_dwordx2 v[110:111], v68, s[10:11] nt
	global_load_dwordx2 v[112:113], v69, s[14:15]
	global_load_dwordx2 v[114:115], v69, s[16:17]
	global_load_dword v118, v71, s[18:19]
	global_load_dwordx2 v[116:117], v68, s[12:13] nt
	s_add_u32 s10, s10, 0x1000
	s_addc_u32 s11, s11, 0
	s_add_u32 s12, s12, 0x1000
	s_addc_u32 s13, s13, 0
	s_add_u32 s14, s14, 0xb800
	s_addc_u32 s15, s15, 0
	s_add_u32 s16, s16, 0xb800
	s_addc_u32 s17, s17, 0
	s_add_u32 s18, s18, 0x80
	s_addc_u32 s19, s19, 0
	global_load_dwordx4 v[120:123], v73, s[22:23] nt
	global_load_dwordx4 v[124:127], v74, s[24:25]
	s_add_u32 s22, s22, 0x2000
	s_addc_u32 s23, s23, 0
	s_add_u32 s24, s24, 0x17000
	s_addc_u32 s25, s25, 0
	global_load_dwordx4 v[128:131], v73, s[22:23] nt
	global_load_dwordx4 v[132:135], v74, s[24:25]
	s_add_u32 s22, s22, 0x2000
	s_addc_u32 s23, s23, 0
	s_add_u32 s24, s24, 0x17000
	s_addc_u32 s25, s25, 0
	s_add_u32 s10, s10, 0x3fc000
	s_addc_u32 s11, s11, 0
	s_add_u32 s12, s12, 0x3fc000
	s_addc_u32 s13, s13, 0
	s_add_u32 s14, s14, 0x2dd2000
	s_addc_u32 s15, s15, 0
	s_add_u32 s16, s16, 0x2dd2000
	s_addc_u32 s17, s17, 0
	s_add_u32 s18, s18, 0x1fe00
	s_addc_u32 s19, s19, 0
	s_add_u32 s22, s22, 0x3fc000
	s_addc_u32 s23, s23, 0
	s_add_u32 s24, s24, 0x2dd2000
	s_addc_u32 s25, s25, 0
.Lpost_step:
	s_waitcnt vmcnt(19)
	v_cndmask_b32_e64 v84, v84, 0, s[44:45]
	v_cndmask_b32_e64 v85, v85, 0, s[44:45]
	v_lshlrev_b32_e32 v2, 16, v80
	v_and_b32_e32 v3, 0xffff0000, v80
	v_lshlrev_b32_e32 v4, 16, v81
	v_and_b32_e32 v5, 0xffff0000, v81
	v_lshlrev_b32_e32 v6, 16, v82
	v_and_b32_e32 v7, 0xffff0000, v82
	v_lshlrev_b32_e32 v8, 16, v83
	v_and_b32_e32 v9, 0xffff0000, v83
	v_lshlrev_b32_e32 v10, 16, v84
	v_and_b32_e32 v11, 0xffff0000, v84
	v_lshlrev_b32_e32 v12, 16, v85
	v_and_b32_e32 v13, 0xffff0000, v85
	v_lshlrev_b32_e32 v14, 16, v86
	v_and_b32_e32 v15, 0xffff0000, v86
	v_lshlrev_b32_e32 v16, 16, v87
	v_and_b32_e32 v17, 0xffff0000, v87
	v_mov_b32_e32 v18, v88
	global_load_dwordx2 v[80:81], v68, s[10:11] nt
	global_load_dwordx2 v[82:83], v69, s[14:15]
	global_load_dwordx2 v[84:85], v69, s[16:17]
	global_load_dword v88, v71, s[18:19]
	global_load_dwordx2 v[86:87], v68, s[12:13] nt
	s_add_u32 s10, s10, 0x1000
	s_addc_u32 s11, s11, 0
	s_add_u32 s12, s12, 0x1000
	s_addc_u32 s13, s13, 0
	s_add_u32 s14, s14, 0xb800
	s_addc_u32 s15, s15, 0
	s_add_u32 s16, s16, 0xb800
	s_addc_u32 s17, s17, 0
	s_add_u32 s18, s18, 0x80
	s_addc_u32 s19, s19, 0
	v_add_f32_e32 v19, v2, v3
	v_add_f32_e32 v20, v4, v5
	v_sub_f32_e32 v10, v10, v6
	v_sub_f32_e32 v11, v11, v7
	v_add_f32_e32 v19, v19, v20
	v_sub_f32_e32 v12, v12, v8
	v_sub_f32_e32 v13, v13, v9
	s_nop 1
	v_add_f32_dpp v19, v19, v19 quad_perm:[1,0,3,2] row_mask:0xf bank_mask:0xf bound_ctrl:1
	s_nop 1
	v_add_f32_dpp v19, v19, v19 quad_perm:[2,3,0,1] row_mask:0xf bank_mask:0xf bound_ctrl:1
	s_nop 1
	v_add_f32_dpp v19, v19, v19 row_half_mirror row_mask:0xf bank_mask:0xf bound_ctrl:1
	s_nop 1
	v_add_f32_dpp v19, v19, v19 row_mirror row_mask:0xf bank_mask:0xf bound_ctrl:1
	v_fmac_f32_e32 v6, v48, v10
	v_fmac_f32_e32 v7, v49, v11
	v_fmac_f32_e32 v8, v50, v12
	v_fmac_f32_e32 v9, v51, v13
	v_mul_f32_e32 v19, 0x3c800000, v19
	v_sub_f32_e32 v2, v2, v19
	v_sub_f32_e32 v3, v3, v19
	v_sub_f32_e32 v4, v4, v19
	v_sub_f32_e32 v5, v5, v19
	v_mul_f32_e32 v20, v2, v2
	v_mul_f32_e32 v21, v3, v3
	v_fmac_f32_e32 v20, v4, v4
	v_fmac_f32_e32 v21, v5, v5
	v_mul_f32_e32 v6, v18, v6
	v_mul_f32_e32 v7, v18, v7
	v_mul_f32_e32 v8, v18, v8
	v_mul_f32_e32 v9, v18, v9
	v_add_f32_e32 v20, v20, v21
	v_add_f32_e32 v6, v44, v6
	v_add_f32_e32 v7, v45, v7
	v_add_f32_e32 v8, v46, v8
	v_add_f32_e32 v9, v47, v9
	s_nop 1
	v_add_f32_dpp v20, v20, v20 quad_perm:[1,0,3,2] row_mask:0xf bank_mask:0xf bound_ctrl:1
	s_nop 1
	v_add_f32_dpp v20, v20, v20 quad_perm:[2,3,0,1] row_mask:0xf bank_mask:0xf bound_ctrl:1
	s_nop 1
	v_add_f32_dpp v20, v20, v20 row_half_mirror row_mask:0xf bank_mask:0xf bound_ctrl:1
	s_nop 1
	v_add_f32_dpp v20, v20, v20 row_mirror row_mask:0xf bank_mask:0xf bound_ctrl:1
	v_mov_b32_e32 v21, 0x3a27c5ac
	v_fmac_f32_e32 v21, 0x3c800000, v20
	v_rsq_f32_e32 v21, v21
	s_nop 0
	v_mul_f32_e32 v2, v2, v21
	v_mul_f32_e32 v3, v3, v21
	v_mul_f32_e32 v4, v4, v21
	v_mul_f32_e32 v5, v5, v21
	v_fmac_f32_e32 v6, v2, v40
	v_fmac_f32_e32 v7, v3, v41
	v_fmac_f32_e32 v8, v4, v42
	v_fmac_f32_e32 v9, v5, v43
	v_mul_f32_e32 v6, v6, v14
	v_mul_f32_e32 v7, v7, v15
	v_mul_f32_e32 v8, v8, v16
	v_mul_f32_e32 v9, v9, v17
	v_cvt_pk_bf16_f32 v20, v6, v7
	v_cvt_pk_bf16_f32 v21, v8, v9
	global_store_dwordx2 v72, v[20:21], s[20:21]
	s_add_u32 s20, s20, 0x2000
	s_addc_u32 s21, s21, 0
	s_waitcnt vmcnt(20)
	v_lshlrev_b32_e32 v2, 16, v90
	v_and_b32_e32 v3, 0xffff0000, v90
	v_lshlrev_b32_e32 v4, 16, v91
	v_and_b32_e32 v5, 0xffff0000, v91
	v_lshlrev_b32_e32 v6, 16, v92
	v_and_b32_e32 v7, 0xffff0000, v92
	v_lshlrev_b32_e32 v8, 16, v93
	v_and_b32_e32 v9, 0xffff0000, v93
	v_lshlrev_b32_e32 v10, 16, v94
	v_and_b32_e32 v11, 0xffff0000, v94
	v_lshlrev_b32_e32 v12, 16, v95
	v_and_b32_e32 v13, 0xffff0000, v95
	v_lshlrev_b32_e32 v14, 16, v96
	v_and_b32_e32 v15, 0xffff0000, v96
	v_lshlrev_b32_e32 v16, 16, v97
	v_and_b32_e32 v17, 0xffff0000, v97
	v_mov_b32_e32 v18, v98
	global_load_dwordx2 v[90:91], v68, s[10:11] nt
	global_load_dwordx2 v[92:93], v69, s[14:15]
	global_load_dwordx2 v[94:95], v69, s[16:17]
	global_load_dword v98, v71, s[18:19]
	global_load_dwordx2 v[96:97], v68, s[12:13] nt
	s_add_u32 s10, s10, 0x1000
	s_addc_u32 s11, s11, 0
	s_add_u32 s12, s12, 0x1000
	s_addc_u32 s13, s13, 0
	s_add_u32 s14, s14, 0xb800
	s_addc_u32 s15, s15, 0
	s_add_u32 s16, s16, 0xb800
	s_addc_u32 s17, s17, 0
	s_add_u32 s18, s18, 0x80
	s_addc_u32 s19, s19, 0
	v_add_f32_e32 v19, v2, v3
	v_add_f32_e32 v20, v4, v5
	v_sub_f32_e32 v10, v10, v6
	v_sub_f32_e32 v11, v11, v7
	v_add_f32_e32 v19, v19, v20
	v_sub_f32_e32 v12, v12, v8
	v_sub_f32_e32 v13, v13, v9
	s_nop 1
	v_add_f32_dpp v19, v19, v19 quad_perm:[1,0,3,2] row_mask:0xf bank_mask:0xf bound_ctrl:1
	s_nop 1
	v_add_f32_dpp v19, v19, v19 quad_perm:[2,3,0,1] row_mask:0xf bank_mask:0xf bound_ctrl:1
	s_nop 1
	v_add_f32_dpp v19, v19, v19 row_half_mirror row_mask:0xf bank_mask:0xf bound_ctrl:1
	s_nop 1
	v_add_f32_dpp v19, v19, v19 row_mirror row_mask:0xf bank_mask:0xf bound_ctrl:1
	v_fmac_f32_e32 v6, v48, v10
	v_fmac_f32_e32 v7, v49, v11
	v_fmac_f32_e32 v8, v50, v12
	v_fmac_f32_e32 v9, v51, v13
	v_mul_f32_e32 v19, 0x3c800000, v19
	v_sub_f32_e32 v2, v2, v19
	v_sub_f32_e32 v3, v3, v19
	v_sub_f32_e32 v4, v4, v19
	v_sub_f32_e32 v5, v5, v19
	v_mul_f32_e32 v20, v2, v2
	v_mul_f32_e32 v21, v3, v3
	v_fmac_f32_e32 v20, v4, v4
	v_fmac_f32_e32 v21, v5, v5
	v_mul_f32_e32 v6, v18, v6
	v_mul_f32_e32 v7, v18, v7
	v_mul_f32_e32 v8, v18, v8
	v_mul_f32_e32 v9, v18, v9
	v_add_f32_e32 v20, v20, v21
	v_add_f32_e32 v6, v44, v6
	v_add_f32_e32 v7, v45, v7
	v_add_f32_e32 v8, v46, v8
	v_add_f32_e32 v9, v47, v9
	s_nop 1
	v_add_f32_dpp v20, v20, v20 quad_perm:[1,0,3,2] row_mask:0xf bank_mask:0xf bound_ctrl:1
	s_nop 1
	v_add_f32_dpp v20, v20, v20 quad_perm:[2,3,0,1] row_mask:0xf bank_mask:0xf bound_ctrl:1
	s_nop 1
	v_add_f32_dpp v20, v20, v20 row_half_mirror row_mask:0xf bank_mask:0xf bound_ctrl:1
	s_nop 1
	v_add_f32_dpp v20, v20, v20 row_mirror row_mask:0xf bank_mask:0xf bound_ctrl:1
	v_mov_b32_e32 v21, 0x3a27c5ac
	v_fmac_f32_e32 v21, 0x3c800000, v20
	v_rsq_f32_e32 v21, v21
	s_nop 0
	v_mul_f32_e32 v2, v2, v21
	v_mul_f32_e32 v3, v3, v21
	v_mul_f32_e32 v4, v4, v21
	v_mul_f32_e32 v5, v5, v21
	v_fmac_f32_e32 v6, v2, v40
	v_fmac_f32_e32 v7, v3, v41
	v_fmac_f32_e32 v8, v4, v42
	v_fmac_f32_e32 v9, v5, v43
	v_mul_f32_e32 v6, v6, v14
	v_mul_f32_e32 v7, v7, v15
	v_mul_f32_e32 v8, v8, v16
	v_mul_f32_e32 v9, v9, v17
	v_cvt_pk_bf16_f32 v20, v6, v7
	v_cvt_pk_bf16_f32 v21, v8, v9
	global_store_dwordx2 v72, v[20:21], s[20:21]
	s_add_u32 s20, s20, 0x2000
	s_addc_u32 s21, s21, 0
	s_waitcnt vmcnt(21)
	v_lshlrev_b32_e32 v2, 16, v100
	v_and_b32_e32 v3, 0xffff0000, v100
	v_lshlrev_b32_e32 v4, 16, v101
	v_and_b32_e32 v5, 0xffff0000, v101
	v_lshlrev_b32_e32 v6, 16, v102
	v_and_b32_e32 v7, 0xffff0000, v102
	v_lshlrev_b32_e32 v8, 16, v103
	v_and_b32_e32 v9, 0xffff0000, v103
	v_lshlrev_b32_e32 v10, 16, v104
	v_and_b32_e32 v11, 0xffff0000, v104
	v_lshlrev_b32_e32 v12, 16, v105
	v_and_b32_e32 v13, 0xffff0000, v105
	v_lshlrev_b32_e32 v14, 16, v106
	v_and_b32_e32 v15, 0xffff0000, v106
	v_lshlrev_b32_e32 v16, 16, v107
	v_and_b32_e32 v17, 0xffff0000, v107
	v_mov_b32_e32 v18, v108
	global_load_dwordx2 v[100:101], v68, s[10:11] nt
	global_load_dwordx2 v[102:103], v69, s[14:15]
	global_load_dwordx2 v[104:105], v69, s[16:17]
	global_load_dword v108, v71, s[18:19]
	global_load_dwordx2 v[106:107], v68, s[12:13] nt
	s_add_u32 s10, s10, 0x1000
	s_addc_u32 s11, s11, 0
	s_add_u32 s12, s12, 0x1000
	s_addc_u32 s13, s13, 0
	s_add_u32 s14, s14, 0xb800
	s_addc_u32 s15, s15, 0
	s_add_u32 s16, s16, 0xb800
	s_addc_u32 s17, s17, 0
	s_add_u32 s18, s18, 0x80
	s_addc_u32 s19, s19, 0
	v_add_f32_e32 v19, v2, v3
	v_add_f32_e32 v20, v4, v5
	v_sub_f32_e32 v10, v10, v6
	v_sub_f32_e32 v11, v11, v7
	v_add_f32_e32 v19, v19, v20
	v_sub_f32_e32 v12, v12, v8
	v_sub_f32_e32 v13, v13, v9
	s_nop 1
	v_add_f32_dpp v19, v19, v19 quad_perm:[1,0,3,2] row_mask:0xf bank_mask:0xf bound_ctrl:1
	s_nop 1
	v_add_f32_dpp v19, v19, v19 quad_perm:[2,3,0,1] row_mask:0xf bank_mask:0xf bound_ctrl:1
	s_nop 1
	v_add_f32_dpp v19, v19, v19 row_half_mirror row_mask:0xf bank_mask:0xf bound_ctrl:1
	s_nop 1
	v_add_f32_dpp v19, v19, v19 row_mirror row_mask:0xf bank_mask:0xf bound_ctrl:1
	v_fmac_f32_e32 v6, v48, v10
	v_fmac_f32_e32 v7, v49, v11
	v_fmac_f32_e32 v8, v50, v12
	v_fmac_f32_e32 v9, v51, v13
	v_mul_f32_e32 v19, 0x3c800000, v19
	v_sub_f32_e32 v2, v2, v19
	v_sub_f32_e32 v3, v3, v19
	v_sub_f32_e32 v4, v4, v19
	v_sub_f32_e32 v5, v5, v19
	v_mul_f32_e32 v20, v2, v2
	v_mul_f32_e32 v21, v3, v3
	v_fmac_f32_e32 v20, v4, v4
	v_fmac_f32_e32 v21, v5, v5
	v_mul_f32_e32 v6, v18, v6
	v_mul_f32_e32 v7, v18, v7
	v_mul_f32_e32 v8, v18, v8
	v_mul_f32_e32 v9, v18, v9
	v_add_f32_e32 v20, v20, v21
	v_add_f32_e32 v6, v44, v6
	v_add_f32_e32 v7, v45, v7
	v_add_f32_e32 v8, v46, v8
	v_add_f32_e32 v9, v47, v9
	s_nop 1
	v_add_f32_dpp v20, v20, v20 quad_perm:[1,0,3,2] row_mask:0xf bank_mask:0xf bound_ctrl:1
	s_nop 1
	v_add_f32_dpp v20, v20, v20 quad_perm:[2,3,0,1] row_mask:0xf bank_mask:0xf bound_ctrl:1
	s_nop 1
	v_add_f32_dpp v20, v20, v20 row_half_mirror row_mask:0xf bank_mask:0xf bound_ctrl:1
	s_nop 1
	v_add_f32_dpp v20, v20, v20 row_mirror row_mask:0xf bank_mask:0xf bound_ctrl:1
	v_mov_b32_e32 v21, 0x3a27c5ac
	v_fmac_f32_e32 v21, 0x3c800000, v20
	v_rsq_f32_e32 v21, v21
	s_nop 0
	v_mul_f32_e32 v2, v2, v21
	v_mul_f32_e32 v3, v3, v21
	v_mul_f32_e32 v4, v4, v21
	v_mul_f32_e32 v5, v5, v21
	v_fmac_f32_e32 v6, v2, v40
	v_fmac_f32_e32 v7, v3, v41
	v_fmac_f32_e32 v8, v4, v42
	v_fmac_f32_e32 v9, v5, v43
	v_mul_f32_e32 v6, v6, v14
	v_mul_f32_e32 v7, v7, v15
	v_mul_f32_e32 v8, v8, v16
	v_mul_f32_e32 v9, v9, v17
	v_cvt_pk_bf16_f32 v20, v6, v7
	v_cvt_pk_bf16_f32 v21, v8, v9
	global_store_dwordx2 v72, v[20:21], s[20:21]
	s_add_u32 s20, s20, 0x2000
	s_addc_u32 s21, s21, 0
	s_waitcnt vmcnt(22)
	v_lshlrev_b32_e32 v2, 16, v110
	v_and_b32_e32 v3, 0xffff0000, v110
	v_lshlrev_b32_e32 v4, 16, v111
	v_and_b32_e32 v5, 0xffff0000, v111
	v_lshlrev_b32_e32 v6, 16, v112
	v_and_b32_e32 v7, 0xffff0000, v112
	v_lshlrev_b32_e32 v8, 16, v113
	v_and_b32_e32 v9, 0xffff0000, v113
	v_lshlrev_b32_e32 v10, 16, v114
	v_and_b32_e32 v11, 0xffff0000, v114
	v_lshlrev_b32_e32 v12, 16, v115
	v_and_b32_e32 v13, 0xffff0000, v115
	v_lshlrev_b32_e32 v14, 16, v116
	v_and_b32_e32 v15, 0xffff0000, v116
	v_lshlrev_b32_e32 v16, 16, v117
	v_and_b32_e32 v17, 0xffff0000, v117
	v_mov_b32_e32 v18, v118
	global_load_dwordx2 v[110:111], v68, s[10:11] nt
	global_load_dwordx2 v[112:113], v69, s[14:15]
	global_load_dwordx2 v[114:115], v69, s[16:17]
	global_load_dword v118, v71, s[18:19]
	global_load_dwordx2 v[116:117], v68, s[12:13] nt
	s_add_u32 s10, s10, 0x1000
	s_addc_u32 s11, s11, 0
	s_add_u32 s12, s12, 0x1000
	s_addc_u32 s13, s13, 0
	s_add_u32 s14, s14, 0xb800
	s_addc_u32 s15, s15, 0
	s_add_u32 s16, s16, 0xb800
	s_addc_u32 s17, s17, 0
	s_add_u32 s18, s18, 0x80
	s_addc_u32 s19, s19, 0
	v_add_f32_e32 v19, v2, v3
	v_add_f32_e32 v20, v4, v5
	v_sub_f32_e32 v10, v10, v6
	v_sub_f32_e32 v11, v11, v7
	v_add_f32_e32 v19, v19, v20
	v_sub_f32_e32 v12, v12, v8
	v_sub_f32_e32 v13, v13, v9
	s_nop 1
	v_add_f32_dpp v19, v19, v19 quad_perm:[1,0,3,2] row_mask:0xf bank_mask:0xf bound_ctrl:1
	s_nop 1
	v_add_f32_dpp v19, v19, v19 quad_perm:[2,3,0,1] row_mask:0xf bank_mask:0xf bound_ctrl:1
	s_nop 1
	v_add_f32_dpp v19, v19, v19 row_half_mirror row_mask:0xf bank_mask:0xf bound_ctrl:1
	s_nop 1
	v_add_f32_dpp v19, v19, v19 row_mirror row_mask:0xf bank_mask:0xf bound_ctrl:1
	v_fmac_f32_e32 v6, v48, v10
	v_fmac_f32_e32 v7, v49, v11
	v_fmac_f32_e32 v8, v50, v12
	v_fmac_f32_e32 v9, v51, v13
	v_mul_f32_e32 v19, 0x3c800000, v19
	v_sub_f32_e32 v2, v2, v19
	v_sub_f32_e32 v3, v3, v19
	v_sub_f32_e32 v4, v4, v19
	v_sub_f32_e32 v5, v5, v19
	v_mul_f32_e32 v20, v2, v2
	v_mul_f32_e32 v21, v3, v3
	v_fmac_f32_e32 v20, v4, v4
	v_fmac_f32_e32 v21, v5, v5
	v_mul_f32_e32 v6, v18, v6
	v_mul_f32_e32 v7, v18, v7
	v_mul_f32_e32 v8, v18, v8
	v_mul_f32_e32 v9, v18, v9
	v_add_f32_e32 v20, v20, v21
	v_add_f32_e32 v6, v44, v6
	v_add_f32_e32 v7, v45, v7
	v_add_f32_e32 v8, v46, v8
	v_add_f32_e32 v9, v47, v9
	s_nop 1
	v_add_f32_dpp v20, v20, v20 quad_perm:[1,0,3,2] row_mask:0xf bank_mask:0xf bound_ctrl:1
	s_nop 1
	v_add_f32_dpp v20, v20, v20 quad_perm:[2,3,0,1] row_mask:0xf bank_mask:0xf bound_ctrl:1
	s_nop 1
	v_add_f32_dpp v20, v20, v20 row_half_mirror row_mask:0xf bank_mask:0xf bound_ctrl:1
	s_nop 1
	v_add_f32_dpp v20, v20, v20 row_mirror row_mask:0xf bank_mask:0xf bound_ctrl:1
	v_mov_b32_e32 v21, 0x3a27c5ac
	v_fmac_f32_e32 v21, 0x3c800000, v20
	v_rsq_f32_e32 v21, v21
	s_nop 0
	v_mul_f32_e32 v2, v2, v21
	v_mul_f32_e32 v3, v3, v21
	v_mul_f32_e32 v4, v4, v21
	v_mul_f32_e32 v5, v5, v21
	v_fmac_f32_e32 v6, v2, v40
	v_fmac_f32_e32 v7, v3, v41
	v_fmac_f32_e32 v8, v4, v42
	v_fmac_f32_e32 v9, v5, v43
	v_mul_f32_e32 v6, v6, v14
	v_mul_f32_e32 v7, v7, v15
	v_mul_f32_e32 v8, v8, v16
	v_mul_f32_e32 v9, v9, v17
	v_cvt_pk_bf16_f32 v20, v6, v7
	v_cvt_pk_bf16_f32 v21, v8, v9
	global_store_dwordx2 v72, v[20:21], s[20:21]
	s_add_u32 s20, s20, 0x2000
	s_addc_u32 s21, s21, 0
	s_waitcnt vmcnt(26)
	v_lshlrev_b32_e32 v2, 16, v120
	v_and_b32_e32 v3, 0xffff0000, v120
	v_lshlrev_b32_e32 v4, 16, v121
	v_and_b32_e32 v5, 0xffff0000, v121
	v_lshlrev_b32_e32 v6, 16, v122
	v_and_b32_e32 v7, 0xffff0000, v122
	v_lshlrev_b32_e32 v8, 16, v123
	v_and_b32_e32 v9, 0xffff0000, v123
	v_lshlrev_b32_e32 v10, 16, v124
	v_and_b32_e32 v11, 0xffff0000, v124
	v_lshlrev_b32_e32 v12, 16, v125
	v_and_b32_e32 v13, 0xffff0000, v125
	v_lshlrev_b32_e32 v14, 16, v126
	v_and_b32_e32 v15, 0xffff0000, v126
	v_lshlrev_b32_e32 v16, 16, v127
	v_and_b32_e32 v17, 0xffff0000, v127
	global_load_dwordx4 v[120:123], v73, s[22:23] nt
	global_load_dwordx4 v[124:127], v74, s[24:25]
	s_add_u32 s22, s22, 0x2000
	s_addc_u32 s23, s23, 0
	s_add_u32 s24, s24, 0x17000
	s_addc_u32 s25, s25, 0
	v_add_f32_e32 v18, v2, v3
	v_add_f32_e32 v19, v4, v5
	v_add_f32_e32 v136, v6, v7
	v_add_f32_e32 v137, v8, v9
	v_add_f32_e32 v18, v18, v19
	v_add_f32_e32 v136, v136, v137
	v_mul_f32_e32 v144, 0xbfb8aa3b, v10
	v_mul_f32_e32 v145, 0xbfb8aa3b, v11
	v_mul_f32_e32 v146, 0xbfb8aa3b, v12
	v_mul_f32_e32 v147, 0xbfb8aa3b, v13
	v_mul_f32_e32 v148, 0xbfb8aa3b, v14
	v_mul_f32_e32 v149, 0xbfb8aa3b, v15
	v_mul_f32_e32 v150, 0xbfb8aa3b, v16
	v_mul_f32_e32 v151, 0xbfb8aa3b, v17
	v_add_f32_e32 v18, v18, v136
	v_exp_f32_e32 v144, v144
	v_exp_f32_e32 v145, v145
	v_exp_f32_e32 v146, v146
	v_exp_f32_e32 v147, v147
	v_exp_f32_e32 v148, v148
	v_exp_f32_e32 v149, v149
	v_exp_f32_e32 v150, v150
	v_exp_f32_e32 v151, v151
	s_nop 1
	v_add_f32_dpp v18, v18, v18 quad_perm:[1,0,3,2] row_mask:0xf bank_mask:0xf bound_ctrl:1
	s_nop 1
	v_add_f32_dpp v18, v18, v18 quad_perm:[2,3,0,1] row_mask:0xf bank_mask:0xf bound_ctrl:1
	s_nop 1
	v_add_f32_dpp v18, v18, v18 row_half_mirror row_mask:0xf bank_mask:0xf bound_ctrl:1
	s_nop 1
	v_add_f32_dpp v18, v18, v18 row_mirror row_mask:0xf bank_mask:0xf bound_ctrl:1
	v_add_f32_e32 v144, 1.0, v144
	v_add_f32_e32 v145, 1.0, v145
	v_add_f32_e32 v146, 1.0, v146
	v_add_f32_e32 v147, 1.0, v147
	v_add_f32_e32 v148, 1.0, v148
	v_add_f32_e32 v149, 1.0, v149
	v_add_f32_e32 v150, 1.0, v150
	v_add_f32_e32 v151, 1.0, v151
	v_mul_f32_e32 v18, 0x3c000000, v18
	v_sub_f32_e32 v2, v2, v18
	v_sub_f32_e32 v3, v3, v18
	v_sub_f32_e32 v4, v4, v18
	v_sub_f32_e32 v5, v5, v18
	v_sub_f32_e32 v6, v6, v18
	v_sub_f32_e32 v7, v7, v18
	v_sub_f32_e32 v8, v8, v18
	v_sub_f32_e32 v9, v9, v18
	v_mul_f32_e32 v19, v2, v2
	v_mul_f32_e32 v136, v3, v3
	v_fmac_f32_e32 v19, v4, v4
	v_fmac_f32_e32 v136, v5, v5
	v_fmac_f32_e32 v19, v6, v6
	v_fmac_f32_e32 v136, v7, v7
	v_fmac_f32_e32 v19, v8, v8
	v_fmac_f32_e32 v136, v9, v9
	v_rcp_f32_e32 v144, v144
	v_rcp_f32_e32 v145, v145
	v_rcp_f32_e32 v146, v146
	v_rcp_f32_e32 v147, v147
	v_rcp_f32_e32 v148, v148
	v_rcp_f32_e32 v149, v149
	v_rcp_f32_e32 v150, v150
	v_rcp_f32_e32 v151, v151
	v_add_f32_e32 v19, v19, v136
	s_nop 1
	v_add_f32_dpp v19, v19, v19 quad_perm:[1,0,3,2] row_mask:0xf bank_mask:0xf bound_ctrl:1
	s_nop 1
	v_add_f32_dpp v19, v19, v19 quad_perm:[2,3,0,1] row_mask:0xf bank_mask:0xf bound_ctrl:1
	s_nop 1
	v_add_f32_dpp v19, v19, v19 row_half_mirror row_mask:0xf bank_mask:0xf bound_ctrl:1
	s_nop 1
	v_add_f32_dpp v19, v19, v19 row_mirror row_mask:0xf bank_mask:0xf bound_ctrl:1
	v_mul_f32_e32 v10, v10, v144
	v_mul_f32_e32 v11, v11, v145
	v_mul_f32_e32 v12, v12, v146
	v_mul_f32_e32 v13, v13, v147
	v_mul_f32_e32 v14, v14, v148
	v_mul_f32_e32 v15, v15, v149
	v_mul_f32_e32 v16, v16, v150
	v_mul_f32_e32 v17, v17, v151
	v_mov_b32_e32 v136, 0x3727c5ac
	v_fmac_f32_e32 v136, 0x3c000000, v19
	v_rsq_f32_e32 v136, v136
	s_nop 0
	v_mul_f32_e32 v2, v2, v136
	v_mul_f32_e32 v3, v3, v136
	v_mul_f32_e32 v4, v4, v136
	v_mul_f32_e32 v5, v5, v136
	v_mul_f32_e32 v6, v6, v136
	v_mul_f32_e32 v7, v7, v136
	v_mul_f32_e32 v8, v8, v136
	v_mul_f32_e32 v9, v9, v136
	v_fma_f32 v2, v2, v52, v60
	v_fma_f32 v3, v3, v53, v61
	v_fma_f32 v4, v4, v54, v62
	v_fma_f32 v5, v5, v55, v63
	v_fma_f32 v6, v6, v56, v64
	v_fma_f32 v7, v7, v57, v65
	v_fma_f32 v8, v8, v58, v66
	v_fma_f32 v9, v9, v59, v67
	v_mul_f32_e32 v2, v2, v10
	v_mul_f32_e32 v3, v3, v11
	v_mul_f32_e32 v4, v4, v12
	v_mul_f32_e32 v5, v5, v13
	v_mul_f32_e32 v6, v6, v14
	v_mul_f32_e32 v7, v7, v15
	v_mul_f32_e32 v8, v8, v16
	v_mul_f32_e32 v9, v9, v17
	v_cvt_pk_bf16_f32 v136, v2, v3
	v_cvt_pk_bf16_f32 v137, v4, v5
	v_cvt_pk_bf16_f32 v138, v6, v7
	v_cvt_pk_bf16_f32 v139, v8, v9
	global_store_dwordx4 v75, v[136:139], s[26:27]
	s_add_u32 s26, s26, 0x4000
	s_addc_u32 s27, s27, 0
	s_waitcnt vmcnt(27)
	v_lshlrev_b32_e32 v2, 16, v128
	v_and_b32_e32 v3, 0xffff0000, v128
	v_lshlrev_b32_e32 v4, 16, v129
	v_and_b32_e32 v5, 0xffff0000, v129
	v_lshlrev_b32_e32 v6, 16, v130
	v_and_b32_e32 v7, 0xffff0000, v130
	v_lshlrev_b32_e32 v8, 16, v131
	v_and_b32_e32 v9, 0xffff0000, v131
	v_lshlrev_b32_e32 v10, 16, v132
	v_and_b32_e32 v11, 0xffff0000, v132
	v_lshlrev_b32_e32 v12, 16, v133
	v_and_b32_e32 v13, 0xffff0000, v133
	v_lshlrev_b32_e32 v14, 16, v134
	v_and_b32_e32 v15, 0xffff0000, v134
	v_lshlrev_b32_e32 v16, 16, v135
	v_and_b32_e32 v17, 0xffff0000, v135
	global_load_dwordx4 v[128:131], v73, s[22:23] nt
	global_load_dwordx4 v[132:135], v74, s[24:25]
	s_add_u32 s22, s22, 0x2000
	s_addc_u32 s23, s23, 0
	s_add_u32 s24, s24, 0x17000
	s_addc_u32 s25, s25, 0
	v_add_f32_e32 v18, v2, v3
	v_add_f32_e32 v19, v4, v5
	v_add_f32_e32 v136, v6, v7
	v_add_f32_e32 v137, v8, v9
	v_add_f32_e32 v18, v18, v19
	v_add_f32_e32 v136, v136, v137
	v_mul_f32_e32 v144, 0xbfb8aa3b, v10
	v_mul_f32_e32 v145, 0xbfb8aa3b, v11
	v_mul_f32_e32 v146, 0xbfb8aa3b, v12
	v_mul_f32_e32 v147, 0xbfb8aa3b, v13
	v_mul_f32_e32 v148, 0xbfb8aa3b, v14
	v_mul_f32_e32 v149, 0xbfb8aa3b, v15
	v_mul_f32_e32 v150, 0xbfb8aa3b, v16
	v_mul_f32_e32 v151, 0xbfb8aa3b, v17
	v_add_f32_e32 v18, v18, v136
	v_exp_f32_e32 v144, v144
	v_exp_f32_e32 v145, v145
	v_exp_f32_e32 v146, v146
	v_exp_f32_e32 v147, v147
	v_exp_f32_e32 v148, v148
	v_exp_f32_e32 v149, v149
	v_exp_f32_e32 v150, v150
	v_exp_f32_e32 v151, v151
	s_nop 1
	v_add_f32_dpp v18, v18, v18 quad_perm:[1,0,3,2] row_mask:0xf bank_mask:0xf bound_ctrl:1
	s_nop 1
	v_add_f32_dpp v18, v18, v18 quad_perm:[2,3,0,1] row_mask:0xf bank_mask:0xf bound_ctrl:1
	s_nop 1
	v_add_f32_dpp v18, v18, v18 row_half_mirror row_mask:0xf bank_mask:0xf bound_ctrl:1
	s_nop 1
	v_add_f32_dpp v18, v18, v18 row_mirror row_mask:0xf bank_mask:0xf bound_ctrl:1
	v_add_f32_e32 v144, 1.0, v144
	v_add_f32_e32 v145, 1.0, v145
	v_add_f32_e32 v146, 1.0, v146
	v_add_f32_e32 v147, 1.0, v147
	v_add_f32_e32 v148, 1.0, v148
	v_add_f32_e32 v149, 1.0, v149
	v_add_f32_e32 v150, 1.0, v150
	v_add_f32_e32 v151, 1.0, v151
	v_mul_f32_e32 v18, 0x3c000000, v18
	v_sub_f32_e32 v2, v2, v18
	v_sub_f32_e32 v3, v3, v18
	v_sub_f32_e32 v4, v4, v18
	v_sub_f32_e32 v5, v5, v18
	v_sub_f32_e32 v6, v6, v18
	v_sub_f32_e32 v7, v7, v18
	v_sub_f32_e32 v8, v8, v18
	v_sub_f32_e32 v9, v9, v18
	v_mul_f32_e32 v19, v2, v2
	v_mul_f32_e32 v136, v3, v3
	v_fmac_f32_e32 v19, v4, v4
	v_fmac_f32_e32 v136, v5, v5
	v_fmac_f32_e32 v19, v6, v6
	v_fmac_f32_e32 v136, v7, v7
	v_fmac_f32_e32 v19, v8, v8
	v_fmac_f32_e32 v136, v9, v9
	v_rcp_f32_e32 v144, v144
	v_rcp_f32_e32 v145, v145
	v_rcp_f32_e32 v146, v146
	v_rcp_f32_e32 v147, v147
	v_rcp_f32_e32 v148, v148
	v_rcp_f32_e32 v149, v149
	v_rcp_f32_e32 v150, v150
	v_rcp_f32_e32 v151, v151
	v_add_f32_e32 v19, v19, v136
	s_nop 1
	v_add_f32_dpp v19, v19, v19 quad_perm:[1,0,3,2] row_mask:0xf bank_mask:0xf bound_ctrl:1
	s_nop 1
	v_add_f32_dpp v19, v19, v19 quad_perm:[2,3,0,1] row_mask:0xf bank_mask:0xf bound_ctrl:1
	s_nop 1
	v_add_f32_dpp v19, v19, v19 row_half_mirror row_mask:0xf bank_mask:0xf bound_ctrl:1
	s_nop 1
	v_add_f32_dpp v19, v19, v19 row_mirror row_mask:0xf bank_mask:0xf bound_ctrl:1
	v_mul_f32_e32 v10, v10, v144
	v_mul_f32_e32 v11, v11, v145
	v_mul_f32_e32 v12, v12, v146
	v_mul_f32_e32 v13, v13, v147
	v_mul_f32_e32 v14, v14, v148
	v_mul_f32_e32 v15, v15, v149
	v_mul_f32_e32 v16, v16, v150
	v_mul_f32_e32 v17, v17, v151
	v_mov_b32_e32 v136, 0x3727c5ac
	v_fmac_f32_e32 v136, 0x3c000000, v19
	v_rsq_f32_e32 v136, v136
	s_nop 0
	v_mul_f32_e32 v2, v2, v136
	v_mul_f32_e32 v3, v3, v136
	v_mul_f32_e32 v4, v4, v136
	v_mul_f32_e32 v5, v5, v136
	v_mul_f32_e32 v6, v6, v136
	v_mul_f32_e32 v7, v7, v136
	v_mul_f32_e32 v8, v8, v136
	v_mul_f32_e32 v9, v9, v136
	v_fma_f32 v2, v2, v52, v60
	v_fma_f32 v3, v3, v53, v61
	v_fma_f32 v4, v4, v54, v62
	v_fma_f32 v5, v5, v55, v63
	v_fma_f32 v6, v6, v56, v64
	v_fma_f32 v7, v7, v57, v65
	v_fma_f32 v8, v8, v58, v66
	v_fma_f32 v9, v9, v59, v67
	v_mul_f32_e32 v2, v2, v10
	v_mul_f32_e32 v3, v3, v11
	v_mul_f32_e32 v4, v4, v12
	v_mul_f32_e32 v5, v5, v13
	v_mul_f32_e32 v6, v6, v14
	v_mul_f32_e32 v7, v7, v15
	v_mul_f32_e32 v8, v8, v16
	v_mul_f32_e32 v9, v9, v17
	v_cvt_pk_bf16_f32 v136, v2, v3
	v_cvt_pk_bf16_f32 v137, v4, v5
	v_cvt_pk_bf16_f32 v138, v6, v7
	v_cvt_pk_bf16_f32 v139, v8, v9
	global_store_dwordx4 v75, v[136:139], s[26:27]
	s_add_u32 s26, s26, 0x4000
	s_addc_u32 s27, s27, 0
	s_add_u32 s10, s10, 0x3fc000
	s_addc_u32 s11, s11, 0
	s_add_u32 s12, s12, 0x3fc000
	s_addc_u32 s13, s13, 0
	s_add_u32 s14, s14, 0x2dd2000
	s_addc_u32 s15, s15, 0
	s_add_u32 s16, s16, 0x2dd2000
	s_addc_u32 s17, s17, 0
	s_add_u32 s18, s18, 0x1fe00
	s_addc_u32 s19, s19, 0
	s_add_u32 s22, s22, 0x3fc000
	s_addc_u32 s23, s23, 0
	s_add_u32 s24, s24, 0x2dd2000
	s_addc_u32 s25, s25, 0
	s_add_u32 s20, s20, 0x7f8000
	s_addc_u32 s21, s21, 0
	s_add_u32 s26, s26, 0x7f8000
	s_addc_u32 s27, s27, 0
	s_sub_u32 s30, s30, 1
	s_cmp_lg_u32 s30, 0
	s_cbranch_scc1 .Lpost_step
	s_waitcnt vmcnt(0)
	s_cmp_ge_u32 s28, 64
	s_cbranch_scc1 .Lpost_done
	s_cmp_ge_u32 s28, 32
	s_cbranch_scc1 .Lpost_pad
	v_readlane_b32 s2, v254, 1
	v_readlane_b32 s3, v254, 2
	s_lshl_b32 s0, s28, 2
	s_add_i32 s0, s0, 0x2000
	s_nop 1
	s_sub_u32 s2, s2, 0x138
	s_subb_u32 s3, s3, 0
	s_load_dwordx2 s[6:7], s[2:3], 0x28
	s_lshl_b32 s1, s0, 11
	s_mul_i32 s30, s0, 0x5c00
	s_lshl_b32 s33, s0, 6
	s_lshl_b32 s44, s0, 12
	s_add_u32 s10, s34, 0x9122200
	s_addc_u32 s11, s35, 0
	s_add_u32 s10, s10, s1
	s_addc_u32 s11, s11, 0
	s_add_u32 s12, s34, 0x1d2e2200
	s_addc_u32 s13, s35, 0
	s_add_u32 s12, s12, s1
	s_addc_u32 s13, s13, 0
	s_add_u32 s14, s34, 0xd322200
	s_addc_u32 s15, s35, 0
	s_add_u32 s14, s14, s30
	s_addc_u32 s15, s15, 0
	s_add_u32 s18, s34, 0x8a70200
	s_addc_u32 s19, s35, 0
	s_add_u32 s18, s18, s33
	s_addc_u32 s19, s19, 0
	s_add_u32 s20, s34, 0xb222200
	s_addc_u32 s21, s35, 0
	s_add_u32 s20, s20, s44
	s_addc_u32 s21, s21, 0
	s_add_u32 s22, s82, s1
	s_addc_u32 s23, s83, 0
	s_mov_b64 s[24:25], s[14:15]
	s_mov_b64 s[26:27], s[20:21]
	s_mul_i32 s0, s28, 0xd200
	s_waitcnt lgkmcnt(0)
	s_add_u32 s6, s6, s0
	s_addc_u32 s7, s7, 0
	global_load_dwordx2 v[80:81], v68, s[10:11] nt
	global_load_dwordx2 v[82:83], v69, s[14:15]
	global_load_dwordx4 v[152:155], v70, s[6:7]
	global_load_dword v88, v71, s[18:19]
	global_load_dwordx2 v[86:87], v68, s[12:13] nt
	s_add_u32 s10, s10, 0x1000
	s_addc_u32 s11, s11, 0
	s_add_u32 s12, s12, 0x1000
	s_addc_u32 s13, s13, 0
	s_add_u32 s14, s14, 0xb800
	s_addc_u32 s15, s15, 0
	s_add_u32 s6, s6, 0x6900
	s_addc_u32 s7, s7, 0
	s_add_u32 s18, s18, 0x80
	s_addc_u32 s19, s19, 0
	global_load_dwordx2 v[90:91], v68, s[10:11] nt
	global_load_dwordx2 v[92:93], v69, s[14:15]
	global_load_dwordx4 v[156:159], v70, s[6:7]
	global_load_dword v98, v71, s[18:19]
	global_load_dwordx2 v[96:97], v68, s[12:13] nt
	s_add_u32 s10, s10, 0x1000
	s_addc_u32 s11, s11, 0
	s_add_u32 s12, s12, 0x1000
	s_addc_u32 s13, s13, 0
	s_add_u32 s14, s14, 0xb800
	s_addc_u32 s15, s15, 0
	s_add_u32 s6, s6, 0x6900
	s_addc_u32 s7, s7, 0
	s_add_u32 s18, s18, 0x80
	s_addc_u32 s19, s19, 0
	global_load_dwordx4 v[120:123], v73, s[22:23] nt
	global_load_dwordx4 v[124:127], v74, s[24:25]
	s_add_u32 s22, s22, 0x2000
	s_addc_u32 s23, s23, 0
	s_add_u32 s24, s24, 0x17000
	s_addc_u32 s25, s25, 0
	s_waitcnt vmcnt(7)
	v_lshlrev_b32_e32 v2, 16, v80
	v_and_b32_e32 v3, 0xffff0000, v80
	v_lshlrev_b32_e32 v4, 16, v81
	v_and_b32_e32 v5, 0xffff0000, v81
	v_lshlrev_b32_e32 v6, 16, v82
	v_and_b32_e32 v7, 0xffff0000, v82
	v_lshlrev_b32_e32 v8, 16, v83
	v_and_b32_e32 v9, 0xffff0000, v83
	v_lshlrev_b32_e32 v14, 16, v86
	v_and_b32_e32 v15, 0xffff0000, v86
	v_lshlrev_b32_e32 v16, 16, v87
	v_and_b32_e32 v17, 0xffff0000, v87
	v_mov_b32_e32 v18, v88
	v_add_f32_e32 v19, v2, v3
	v_add_f32_e32 v20, v4, v5
	v_sub_f32_e32 v152, v152, v6
	v_sub_f32_e32 v153, v153, v7
	v_add_f32_e32 v19, v19, v20
	v_sub_f32_e32 v154, v154, v8
	v_sub_f32_e32 v155, v155, v9
	s_nop 1
	v_add_f32_dpp v19, v19, v19 quad_perm:[1,0,3,2] row_mask:0xf bank_mask:0xf bound_ctrl:1
	s_nop 1
	v_add_f32_dpp v19, v19, v19 quad_perm:[2,3,0,1] row_mask:0xf bank_mask:0xf bound_ctrl:1
	s_nop 1
	v_add_f32_dpp v19, v19, v19 row_half_mirror row_mask:0xf bank_mask:0xf bound_ctrl:1
	s_nop 1
	v_add_f32_dpp v19, v19, v19 row_mirror row_mask:0xf bank_mask:0xf bound_ctrl:1
	v_fmac_f32_e32 v6, v48, v152
	v_fmac_f32_e32 v7, v49, v153
	v_fmac_f32_e32 v8, v50, v154
	v_fmac_f32_e32 v9, v51, v155
	v_mul_f32_e32 v19, 0x3c800000, v19
	v_sub_f32_e32 v2, v2, v19
	v_sub_f32_e32 v3, v3, v19
	v_sub_f32_e32 v4, v4, v19
	v_sub_f32_e32 v5, v5, v19
	v_mul_f32_e32 v20, v2, v2
	v_mul_f32_e32 v21, v3, v3
	v_fmac_f32_e32 v20, v4, v4
	v_fmac_f32_e32 v21, v5, v5
	v_mul_f32_e32 v6, v18, v6
	v_mul_f32_e32 v7, v18, v7
	v_mul_f32_e32 v8, v18, v8
	v_mul_f32_e32 v9, v18, v9
	v_add_f32_e32 v20, v20, v21
	v_add_f32_e32 v6, v44, v6
	v_add_f32_e32 v7, v45, v7
	v_add_f32_e32 v8, v46, v8
	v_add_f32_e32 v9, v47, v9
	s_nop 1
	v_add_f32_dpp v20, v20, v20 quad_perm:[1,0,3,2] row_mask:0xf bank_mask:0xf bound_ctrl:1
	s_nop 1
	v_add_f32_dpp v20, v20, v20 quad_perm:[2,3,0,1] row_mask:0xf bank_mask:0xf bound_ctrl:1
	s_nop 1
	v_add_f32_dpp v20, v20, v20 row_half_mirror row_mask:0xf bank_mask:0xf bound_ctrl:1
	s_nop 1
	v_add_f32_dpp v20, v20, v20 row_mirror row_mask:0xf bank_mask:0xf bound_ctrl:1
	v_mov_b32_e32 v21, 0x3a27c5ac
	v_fmac_f32_e32 v21, 0x3c800000, v20
	v_rsq_f32_e32 v21, v21
	s_nop 0
	v_mul_f32_e32 v2, v2, v21
	v_mul_f32_e32 v3, v3, v21
	v_mul_f32_e32 v4, v4, v21
	v_mul_f32_e32 v5, v5, v21
	v_fmac_f32_e32 v6, v2, v40
	v_fmac_f32_e32 v7, v3, v41
	v_fmac_f32_e32 v8, v4, v42
	v_fmac_f32_e32 v9, v5, v43
	v_mul_f32_e32 v6, v6, v14
	v_mul_f32_e32 v7, v7, v15
	v_mul_f32_e32 v8, v8, v16
	v_mul_f32_e32 v9, v9, v17
	v_cvt_pk_bf16_f32 v20, v6, v7
	v_cvt_pk_bf16_f32 v21, v8, v9
	global_store_dwordx2 v72, v[20:21], s[20:21]
	s_add_u32 s20, s20, 0x2000
	s_addc_u32 s21, s21, 0
	s_waitcnt vmcnt(3)
	v_lshlrev_b32_e32 v2, 16, v90
	v_and_b32_e32 v3, 0xffff0000, v90
	v_lshlrev_b32_e32 v4, 16, v91
	v_and_b32_e32 v5, 0xffff0000, v91
	v_lshlrev_b32_e32 v6, 16, v92
	v_and_b32_e32 v7, 0xffff0000, v92
	v_lshlrev_b32_e32 v8, 16, v93
	v_and_b32_e32 v9, 0xffff0000, v93
	v_lshlrev_b32_e32 v14, 16, v96
	v_and_b32_e32 v15, 0xffff0000, v96
	v_lshlrev_b32_e32 v16, 16, v97
	v_and_b32_e32 v17, 0xffff0000, v97
	v_mov_b32_e32 v18, v98
	v_add_f32_e32 v19, v2, v3
	v_add_f32_e32 v20, v4, v5
	v_sub_f32_e32 v156, v156, v6
	v_sub_f32_e32 v157, v157, v7
	v_add_f32_e32 v19, v19, v20
	v_sub_f32_e32 v158, v158, v8
	v_sub_f32_e32 v159, v159, v9
	s_nop 1
	v_add_f32_dpp v19, v19, v19 quad_perm:[1,0,3,2] row_mask:0xf bank_mask:0xf bound_ctrl:1
	s_nop 1
	v_add_f32_dpp v19, v19, v19 quad_perm:[2,3,0,1] row_mask:0xf bank_mask:0xf bound_ctrl:1
	s_nop 1
	v_add_f32_dpp v19, v19, v19 row_half_mirror row_mask:0xf bank_mask:0xf bound_ctrl:1
	s_nop 1
	v_add_f32_dpp v19, v19, v19 row_mirror row_mask:0xf bank_mask:0xf bound_ctrl:1
	v_fmac_f32_e32 v6, v48, v156
	v_fmac_f32_e32 v7, v49, v157
	v_fmac_f32_e32 v8, v50, v158
	v_fmac_f32_e32 v9, v51, v159
	v_mul_f32_e32 v19, 0x3c800000, v19
	v_sub_f32_e32 v2, v2, v19
	v_sub_f32_e32 v3, v3, v19
	v_sub_f32_e32 v4, v4, v19
	v_sub_f32_e32 v5, v5, v19
	v_mul_f32_e32 v20, v2, v2
	v_mul_f32_e32 v21, v3, v3
	v_fmac_f32_e32 v20, v4, v4
	v_fmac_f32_e32 v21, v5, v5
	v_mul_f32_e32 v6, v18, v6
	v_mul_f32_e32 v7, v18, v7
	v_mul_f32_e32 v8, v18, v8
	v_mul_f32_e32 v9, v18, v9
	v_add_f32_e32 v20, v20, v21
	v_add_f32_e32 v6, v44, v6
	v_add_f32_e32 v7, v45, v7
	v_add_f32_e32 v8, v46, v8
	v_add_f32_e32 v9, v47, v9
	s_nop 1
	v_add_f32_dpp v20, v20, v20 quad_perm:[1,0,3,2] row_mask:0xf bank_mask:0xf bound_ctrl:1
	s_nop 1
	v_add_f32_dpp v20, v20, v20 quad_perm:[2,3,0,1] row_mask:0xf bank_mask:0xf bound_ctrl:1
	s_nop 1
	v_add_f32_dpp v20, v20, v20 row_half_mirror row_mask:0xf bank_mask:0xf bound_ctrl:1
	s_nop 1
	v_add_f32_dpp v20, v20, v20 row_mirror row_mask:0xf bank_mask:0xf bound_ctrl:1
	v_mov_b32_e32 v21, 0x3a27c5ac
	v_fmac_f32_e32 v21, 0x3c800000, v20
	v_rsq_f32_e32 v21, v21
	s_nop 0
	v_mul_f32_e32 v2, v2, v21
	v_mul_f32_e32 v3, v3, v21
	v_mul_f32_e32 v4, v4, v21
	v_mul_f32_e32 v5, v5, v21
	v_fmac_f32_e32 v6, v2, v40
	v_fmac_f32_e32 v7, v3, v41
	v_fmac_f32_e32 v8, v4, v42
	v_fmac_f32_e32 v9, v5, v43
	v_mul_f32_e32 v6, v6, v14
	v_mul_f32_e32 v7, v7, v15
	v_mul_f32_e32 v8, v8, v16
	v_mul_f32_e32 v9, v9, v17
	v_cvt_pk_bf16_f32 v20, v6, v7
	v_cvt_pk_bf16_f32 v21, v8, v9
	global_store_dwordx2 v72, v[20:21], s[20:21]
	s_add_u32 s20, s20, 0x2000
	s_addc_u32 s21, s21, 0
	s_waitcnt vmcnt(2)
	v_lshlrev_b32_e32 v2, 16, v120
	v_and_b32_e32 v3, 0xffff0000, v120
	v_lshlrev_b32_e32 v4, 16, v121
	v_and_b32_e32 v5, 0xffff0000, v121
	v_lshlrev_b32_e32 v6, 16, v122
	v_and_b32_e32 v7, 0xffff0000, v122
	v_lshlrev_b32_e32 v8, 16, v123
	v_and_b32_e32 v9, 0xffff0000, v123
	v_lshlrev_b32_e32 v10, 16, v124
	v_and_b32_e32 v11, 0xffff0000, v124
	v_lshlrev_b32_e32 v12, 16, v125
	v_and_b32_e32 v13, 0xffff0000, v125
	v_lshlrev_b32_e32 v14, 16, v126
	v_and_b32_e32 v15, 0xffff0000, v126
	v_lshlrev_b32_e32 v16, 16, v127
	v_and_b32_e32 v17, 0xffff0000, v127
	v_add_f32_e32 v18, v2, v3
	v_add_f32_e32 v19, v4, v5
	v_add_f32_e32 v136, v6, v7
	v_add_f32_e32 v137, v8, v9
	v_add_f32_e32 v18, v18, v19
	v_add_f32_e32 v136, v136, v137
	v_mul_f32_e32 v144, 0xbfb8aa3b, v10
	v_mul_f32_e32 v145, 0xbfb8aa3b, v11
	v_mul_f32_e32 v146, 0xbfb8aa3b, v12
	v_mul_f32_e32 v147, 0xbfb8aa3b, v13
	v_mul_f32_e32 v148, 0xbfb8aa3b, v14
	v_mul_f32_e32 v149, 0xbfb8aa3b, v15
	v_mul_f32_e32 v150, 0xbfb8aa3b, v16
	v_mul_f32_e32 v151, 0xbfb8aa3b, v17
	v_add_f32_e32 v18, v18, v136
	v_exp_f32_e32 v144, v144
	v_exp_f32_e32 v145, v145
	v_exp_f32_e32 v146, v146
	v_exp_f32_e32 v147, v147
	v_exp_f32_e32 v148, v148
	v_exp_f32_e32 v149, v149
	v_exp_f32_e32 v150, v150
	v_exp_f32_e32 v151, v151
	s_nop 1
	v_add_f32_dpp v18, v18, v18 quad_perm:[1,0,3,2] row_mask:0xf bank_mask:0xf bound_ctrl:1
	s_nop 1
	v_add_f32_dpp v18, v18, v18 quad_perm:[2,3,0,1] row_mask:0xf bank_mask:0xf bound_ctrl:1
	s_nop 1
	v_add_f32_dpp v18, v18, v18 row_half_mirror row_mask:0xf bank_mask:0xf bound_ctrl:1
	s_nop 1
	v_add_f32_dpp v18, v18, v18 row_mirror row_mask:0xf bank_mask:0xf bound_ctrl:1
	v_add_f32_e32 v144, 1.0, v144
	v_add_f32_e32 v145, 1.0, v145
	v_add_f32_e32 v146, 1.0, v146
	v_add_f32_e32 v147, 1.0, v147
	v_add_f32_e32 v148, 1.0, v148
	v_add_f32_e32 v149, 1.0, v149
	v_add_f32_e32 v150, 1.0, v150
	v_add_f32_e32 v151, 1.0, v151
	v_mul_f32_e32 v18, 0x3c000000, v18
	v_sub_f32_e32 v2, v2, v18
	v_sub_f32_e32 v3, v3, v18
	v_sub_f32_e32 v4, v4, v18
	v_sub_f32_e32 v5, v5, v18
	v_sub_f32_e32 v6, v6, v18
	v_sub_f32_e32 v7, v7, v18
	v_sub_f32_e32 v8, v8, v18
	v_sub_f32_e32 v9, v9, v18
	v_mul_f32_e32 v19, v2, v2
	v_mul_f32_e32 v136, v3, v3
	v_fmac_f32_e32 v19, v4, v4
	v_fmac_f32_e32 v136, v5, v5
	v_fmac_f32_e32 v19, v6, v6
	v_fmac_f32_e32 v136, v7, v7
	v_fmac_f32_e32 v19, v8, v8
	v_fmac_f32_e32 v136, v9, v9
	v_rcp_f32_e32 v144, v144
	v_rcp_f32_e32 v145, v145
	v_rcp_f32_e32 v146, v146
	v_rcp_f32_e32 v147, v147
	v_rcp_f32_e32 v148, v148
	v_rcp_f32_e32 v149, v149
	v_rcp_f32_e32 v150, v150
	v_rcp_f32_e32 v151, v151
	v_add_f32_e32 v19, v19, v136
	s_nop 1
	v_add_f32_dpp v19, v19, v19 quad_perm:[1,0,3,2] row_mask:0xf bank_mask:0xf bound_ctrl:1
	s_nop 1
	v_add_f32_dpp v19, v19, v19 quad_perm:[2,3,0,1] row_mask:0xf bank_mask:0xf bound_ctrl:1
	s_nop 1
	v_add_f32_dpp v19, v19, v19 row_half_mirror row_mask:0xf bank_mask:0xf bound_ctrl:1
	s_nop 1
	v_add_f32_dpp v19, v19, v19 row_mirror row_mask:0xf bank_mask:0xf bound_ctrl:1
	v_mul_f32_e32 v10, v10, v144
	v_mul_f32_e32 v11, v11, v145
	v_mul_f32_e32 v12, v12, v146
	v_mul_f32_e32 v13, v13, v147
	v_mul_f32_e32 v14, v14, v148
	v_mul_f32_e32 v15, v15, v149
	v_mul_f32_e32 v16, v16, v150
	v_mul_f32_e32 v17, v17, v151
	v_mov_b32_e32 v136, 0x3727c5ac
	v_fmac_f32_e32 v136, 0x3c000000, v19
	v_rsq_f32_e32 v136, v136
	s_nop 0
	v_mul_f32_e32 v2, v2, v136
	v_mul_f32_e32 v3, v3, v136
	v_mul_f32_e32 v4, v4, v136
	v_mul_f32_e32 v5, v5, v136
	v_mul_f32_e32 v6, v6, v136
	v_mul_f32_e32 v7, v7, v136
	v_mul_f32_e32 v8, v8, v136
	v_mul_f32_e32 v9, v9, v136
	v_fma_f32 v2, v2, v52, v60
	v_fma_f32 v3, v3, v53, v61
	v_fma_f32 v4, v4, v54, v62
	v_fma_f32 v5, v5, v55, v63
	v_fma_f32 v6, v6, v56, v64
	v_fma_f32 v7, v7, v57, v65
	v_fma_f32 v8, v8, v58, v66
	v_fma_f32 v9, v9, v59, v67
	v_mul_f32_e32 v2, v2, v10
	v_mul_f32_e32 v3, v3, v11
	v_mul_f32_e32 v4, v4, v12
	v_mul_f32_e32 v5, v5, v13
	v_mul_f32_e32 v6, v6, v14
	v_mul_f32_e32 v7, v7, v15
	v_mul_f32_e32 v8, v8, v16
	v_mul_f32_e32 v9, v9, v17
	v_cvt_pk_bf16_f32 v136, v2, v3
	v_cvt_pk_bf16_f32 v137, v4, v5
	v_cvt_pk_bf16_f32 v138, v6, v7
	v_cvt_pk_bf16_f32 v139, v8, v9
	global_store_dwordx4 v75, v[136:139], s[26:27]
	s_add_u32 s26, s26, 0x4000
	s_addc_u32 s27, s27, 0
	s_branch .Lpost_done
.Lpost_pad:
	s_sub_u32 s0, s28, 32
	s_lshl_b32 s0, s0, 14
	s_add_u32 s0, s0, 0x2080000
	s_add_u32 s20, s34, 0xb222200
	s_addc_u32 s21, s35, 0
	s_add_u32 s20, s20, s0
	s_addc_u32 s21, s21, 0
	v_lshlrev_b32_e32 v2, 5, v34
	v_mov_b32_e32 v4, 0
	v_mov_b32_e32 v5, 0
	v_mov_b32_e32 v6, 0
	v_mov_b32_e32 v7, 0
	global_store_dwordx4 v2, v[4:7], s[20:21]
	global_store_dwordx4 v2, v[4:7], s[20:21] offset:16
.Lpost_done:
	s_branch .LBB0_1915
